# A + software-pipelined K-fragment ds_reads in the 4 in-loop attention QK^T blocks (3-4 register quads instead of 1)
# baseline (speedup 1.0000x reference)
; #define LAS __attribute__((address_space(3)))
; __device__ __forceinline__ void qkt(f32x16& p0, f32x16& p1, const LAS char* Ks, const bf16x8* qr, int r32, int hi) {
;     p0 = f32x16{}; p1 = f32x16{};
; #pragma unroll
;     for (int d0 = 0; d0 < 8; ++d0) { const int cb = (d0 * 16 + hi * 8) * 2;
;         const bf16x8 b0 = *(const LAS bf16x8*)(Ks + KSWZ(r32, cb));
;         const bf16x8 b1 = *(const LAS bf16x8*)(Ks + KSWZ(32 + r32, cb));
;         p0 = __builtin_amdgcn_mfma_f32_32x32x16_bf16(b0, qr[d0], p0, 0, 0, 0);
;         p1 = __builtin_amdgcn_mfma_f32_32x32x16_bf16(b1, qr[d0], p1, 0, 0, 0); }
; }
.LBB0_951:
	s_andn2_b64 vcc, exec, s[8:9]
	s_cbranch_vccnz .LBB0_953
	v_add_u32_e32 v2, v217, v233
	ds_read_b128 v[4:7], v2 offset:49152
	ds_read_b128 v[8:11], v2 offset:57344
	v_add_u32_e32 v16, v217, v232
	ds_read_b128 v[12:15], v16 offset:49152
	s_waitcnt lgkmcnt(2)
	v_mfma_f32_32x32x16_bf16 v[114:129], v[4:7], v[174:177], 0
	ds_read_b128 v[20:23], v16 offset:57344
	s_waitcnt lgkmcnt(2)
	v_mfma_f32_32x32x16_bf16 v[98:113], v[8:11], v[174:177], 0
	v_add_u32_e32 v2, v217, v231
	ds_read_b128 v[4:7], v2 offset:49152
	s_waitcnt lgkmcnt(2)
	v_mfma_f32_32x32x16_bf16 v[114:129], v[12:15], v[170:173], v[114:129]
	ds_read_b128 v[8:11], v2 offset:57344
	s_waitcnt lgkmcnt(2)
	v_mfma_f32_32x32x16_bf16 v[98:113], v[20:23], v[170:173], v[98:113]
	v_add_u32_e32 v16, v217, v230
	ds_read_b128 v[12:15], v16 offset:49152
	s_waitcnt lgkmcnt(2)
	v_mfma_f32_32x32x16_bf16 v[114:129], v[4:7], v[166:169], v[114:129]
	ds_read_b128 v[20:23], v16 offset:57344
	s_waitcnt lgkmcnt(2)
	v_mfma_f32_32x32x16_bf16 v[98:113], v[8:11], v[166:169], v[98:113]
	v_add_u32_e32 v2, v217, v229
	ds_read_b128 v[4:7], v2 offset:49152
	s_waitcnt lgkmcnt(2)
	v_mfma_f32_32x32x16_bf16 v[114:129], v[12:15], v[162:165], v[114:129]
	ds_read_b128 v[8:11], v2 offset:57344
	s_waitcnt lgkmcnt(2)
	v_mfma_f32_32x32x16_bf16 v[98:113], v[20:23], v[162:165], v[98:113]
	v_add_u32_e32 v16, v217, v228
	ds_read_b128 v[12:15], v16 offset:49152
	s_waitcnt lgkmcnt(2)
	v_mfma_f32_32x32x16_bf16 v[114:129], v[4:7], v[158:161], v[114:129]
	ds_read_b128 v[20:23], v16 offset:57344
	s_waitcnt lgkmcnt(2)
	v_mfma_f32_32x32x16_bf16 v[98:113], v[8:11], v[158:161], v[98:113]
	v_add_u32_e32 v2, v217, v227
	ds_read_b128 v[4:7], v2 offset:49152
	s_waitcnt lgkmcnt(2)
	v_mfma_f32_32x32x16_bf16 v[114:129], v[12:15], v[154:157], v[114:129]
	ds_read_b128 v[8:11], v2 offset:57344
	s_waitcnt lgkmcnt(2)
	v_mfma_f32_32x32x16_bf16 v[98:113], v[20:23], v[154:157], v[98:113]
	v_add_u32_e32 v16, v217, v226
	ds_read_b128 v[12:15], v16 offset:49152
	s_waitcnt lgkmcnt(2)
	v_mfma_f32_32x32x16_bf16 v[114:129], v[4:7], v[150:153], v[114:129]
	ds_read_b128 v[20:23], v16 offset:57344
	s_waitcnt lgkmcnt(2)
	v_mfma_f32_32x32x16_bf16 v[98:113], v[8:11], v[150:153], v[98:113]
	s_waitcnt lgkmcnt(1)
	v_mfma_f32_32x32x16_bf16 v[114:129], v[12:15], v[146:149], v[114:129]
	s_waitcnt lgkmcnt(0)
	v_mfma_f32_32x32x16_bf16 v[98:113], v[20:23], v[146:149], v[98:113]
	s_branch .LBB0_954

; #define LAS __attribute__((address_space(3)))
; __device__ __forceinline__ void qkt(f32x16& p0, f32x16& p1, const LAS char* Ks, const bf16x8* qr, int r32, int hi) {
;     p0 = f32x16{}; p1 = f32x16{};
; #pragma unroll
;     for (int d0 = 0; d0 < 8; ++d0) { const int cb = (d0 * 16 + hi * 8) * 2;
;         const bf16x8 b0 = *(const LAS bf16x8*)(Ks + KSWZ(r32, cb));
;         const bf16x8 b1 = *(const LAS bf16x8*)(Ks + KSWZ(32 + r32, cb));
;         p0 = __builtin_amdgcn_mfma_f32_32x32x16_bf16(b0, qr[d0], p0, 0, 0, 0);
;         p1 = __builtin_amdgcn_mfma_f32_32x32x16_bf16(b1, qr[d0], p1, 0, 0, 0); }
; }
.LBB0_1031:
	s_andn2_b64 vcc, exec, s[36:37]
	s_cbranch_vccnz .LBB0_1033
	v_add_u32_e32 v19, v217, v233
	ds_read_b128 v[20:23], v19 offset:32768
	ds_read_b128 v[24:27], v19 offset:40960
	s_waitcnt lgkmcnt(1)
	v_mfma_f32_32x32x16_bf16 v[130:145], v[20:23], v[174:177], 0
	v_add_u32_e32 v32, v217, v232
	ds_read_b128 v[28:31], v32 offset:32768
	s_waitcnt lgkmcnt(1)
	v_mfma_f32_32x32x16_bf16 v[114:129], v[24:27], v[174:177], 0
	ds_read_b128 v[20:23], v32 offset:40960
	s_waitcnt lgkmcnt(1)
	v_mfma_f32_32x32x16_bf16 v[130:145], v[28:31], v[170:173], v[130:145]
	v_add_u32_e32 v19, v217, v231
	ds_read_b128 v[24:27], v19 offset:32768
	s_waitcnt lgkmcnt(1)
	v_mfma_f32_32x32x16_bf16 v[114:129], v[20:23], v[170:173], v[114:129]
	ds_read_b128 v[28:31], v19 offset:40960
	s_waitcnt lgkmcnt(1)
	v_mfma_f32_32x32x16_bf16 v[130:145], v[24:27], v[166:169], v[130:145]
	v_add_u32_e32 v32, v217, v230
	ds_read_b128 v[20:23], v32 offset:32768
	s_waitcnt lgkmcnt(1)
	v_mfma_f32_32x32x16_bf16 v[114:129], v[28:31], v[166:169], v[114:129]
	ds_read_b128 v[24:27], v32 offset:40960
	s_waitcnt lgkmcnt(1)
	v_mfma_f32_32x32x16_bf16 v[130:145], v[20:23], v[162:165], v[130:145]
	v_add_u32_e32 v19, v217, v229
	ds_read_b128 v[28:31], v19 offset:32768
	s_waitcnt lgkmcnt(1)
	v_mfma_f32_32x32x16_bf16 v[114:129], v[24:27], v[162:165], v[114:129]
	ds_read_b128 v[20:23], v19 offset:40960
	s_waitcnt lgkmcnt(1)
	v_mfma_f32_32x32x16_bf16 v[130:145], v[28:31], v[158:161], v[130:145]
	v_add_u32_e32 v32, v217, v228
	ds_read_b128 v[24:27], v32 offset:32768
	s_waitcnt lgkmcnt(1)
	v_mfma_f32_32x32x16_bf16 v[114:129], v[20:23], v[158:161], v[114:129]
	ds_read_b128 v[28:31], v32 offset:40960
	s_waitcnt lgkmcnt(1)
	v_mfma_f32_32x32x16_bf16 v[130:145], v[24:27], v[154:157], v[130:145]
	v_add_u32_e32 v19, v217, v227
	ds_read_b128 v[20:23], v19 offset:32768
	s_waitcnt lgkmcnt(1)
	v_mfma_f32_32x32x16_bf16 v[114:129], v[28:31], v[154:157], v[114:129]
	ds_read_b128 v[24:27], v19 offset:40960
	s_waitcnt lgkmcnt(1)
	v_mfma_f32_32x32x16_bf16 v[130:145], v[20:23], v[150:153], v[130:145]
	v_add_u32_e32 v32, v217, v226
	ds_read_b128 v[28:31], v32 offset:32768
	s_waitcnt lgkmcnt(1)
	v_mfma_f32_32x32x16_bf16 v[114:129], v[24:27], v[150:153], v[114:129]
	ds_read_b128 v[20:23], v32 offset:40960
	s_waitcnt lgkmcnt(1)
	v_mfma_f32_32x32x16_bf16 v[130:145], v[28:31], v[146:149], v[130:145]
	s_waitcnt lgkmcnt(0)
	v_mfma_f32_32x32x16_bf16 v[114:129], v[20:23], v[146:149], v[114:129]
	s_branch .LBB0_1034

; #define LAS __attribute__((address_space(3)))
; __device__ __forceinline__ void qkt(f32x16& p0, f32x16& p1, const LAS char* Ks, const bf16x8* qr, int r32, int hi) {
;     p0 = f32x16{}; p1 = f32x16{};
; #pragma unroll
;     for (int d0 = 0; d0 < 8; ++d0) { const int cb = (d0 * 16 + hi * 8) * 2;
;         const bf16x8 b0 = *(const LAS bf16x8*)(Ks + KSWZ(r32, cb));
;         const bf16x8 b1 = *(const LAS bf16x8*)(Ks + KSWZ(32 + r32, cb));
;         p0 = __builtin_amdgcn_mfma_f32_32x32x16_bf16(b0, qr[d0], p0, 0, 0, 0);
;         p1 = __builtin_amdgcn_mfma_f32_32x32x16_bf16(b1, qr[d0], p1, 0, 0, 0); }
; }
.LBB0_2485:
	s_andn2_b64 vcc, exec, s[20:21]
	s_cbranch_vccnz .LBB0_2487
	v_add_u32_e32 v2, v217, v233
	ds_read_b128 v[4:7], v2 offset:49152
	ds_read_b128 v[8:11], v2 offset:57344
	v_add_u32_e32 v16, v217, v232
	ds_read_b128 v[12:15], v16 offset:49152
	s_waitcnt lgkmcnt(2)
	v_mfma_f32_32x32x16_bf16 v[114:129], v[4:7], v[174:177], 0
	ds_read_b128 v[20:23], v16 offset:57344
	s_waitcnt lgkmcnt(2)
	v_mfma_f32_32x32x16_bf16 v[98:113], v[8:11], v[174:177], 0
	v_add_u32_e32 v2, v217, v231
	ds_read_b128 v[4:7], v2 offset:49152
	s_waitcnt lgkmcnt(2)
	v_mfma_f32_32x32x16_bf16 v[114:129], v[12:15], v[170:173], v[114:129]
	ds_read_b128 v[8:11], v2 offset:57344
	s_waitcnt lgkmcnt(2)
	v_mfma_f32_32x32x16_bf16 v[98:113], v[20:23], v[170:173], v[98:113]
	v_add_u32_e32 v16, v217, v230
	ds_read_b128 v[12:15], v16 offset:49152
	s_waitcnt lgkmcnt(2)
	v_mfma_f32_32x32x16_bf16 v[114:129], v[4:7], v[166:169], v[114:129]
	ds_read_b128 v[20:23], v16 offset:57344
	s_waitcnt lgkmcnt(2)
	v_mfma_f32_32x32x16_bf16 v[98:113], v[8:11], v[166:169], v[98:113]
	v_add_u32_e32 v2, v217, v229
	ds_read_b128 v[4:7], v2 offset:49152
	s_waitcnt lgkmcnt(2)
	v_mfma_f32_32x32x16_bf16 v[114:129], v[12:15], v[162:165], v[114:129]
	ds_read_b128 v[8:11], v2 offset:57344
	s_waitcnt lgkmcnt(2)
	v_mfma_f32_32x32x16_bf16 v[98:113], v[20:23], v[162:165], v[98:113]
	v_add_u32_e32 v16, v217, v228
	ds_read_b128 v[12:15], v16 offset:49152
	s_waitcnt lgkmcnt(2)
	v_mfma_f32_32x32x16_bf16 v[114:129], v[4:7], v[158:161], v[114:129]
	ds_read_b128 v[20:23], v16 offset:57344
	s_waitcnt lgkmcnt(2)
	v_mfma_f32_32x32x16_bf16 v[98:113], v[8:11], v[158:161], v[98:113]
	v_add_u32_e32 v2, v217, v227
	ds_read_b128 v[4:7], v2 offset:49152
	s_waitcnt lgkmcnt(2)
	v_mfma_f32_32x32x16_bf16 v[114:129], v[12:15], v[154:157], v[114:129]
	ds_read_b128 v[8:11], v2 offset:57344
	s_waitcnt lgkmcnt(2)
	v_mfma_f32_32x32x16_bf16 v[98:113], v[20:23], v[154:157], v[98:113]
	v_add_u32_e32 v16, v217, v226
	ds_read_b128 v[12:15], v16 offset:49152
	s_waitcnt lgkmcnt(2)
	v_mfma_f32_32x32x16_bf16 v[114:129], v[4:7], v[150:153], v[114:129]
	ds_read_b128 v[20:23], v16 offset:57344
	s_waitcnt lgkmcnt(2)
	v_mfma_f32_32x32x16_bf16 v[98:113], v[8:11], v[150:153], v[98:113]
	s_waitcnt lgkmcnt(1)
	v_mfma_f32_32x32x16_bf16 v[114:129], v[12:15], v[146:149], v[114:129]
	s_waitcnt lgkmcnt(0)
	v_mfma_f32_32x32x16_bf16 v[98:113], v[20:23], v[146:149], v[98:113]
	s_branch .LBB0_2488

; #define LAS __attribute__((address_space(3)))
; __device__ __forceinline__ void qkt(f32x16& p0, f32x16& p1, const LAS char* Ks, const bf16x8* qr, int r32, int hi) {
;     p0 = f32x16{}; p1 = f32x16{};
; #pragma unroll
;     for (int d0 = 0; d0 < 8; ++d0) { const int cb = (d0 * 16 + hi * 8) * 2;
;         const bf16x8 b0 = *(const LAS bf16x8*)(Ks + KSWZ(r32, cb));
;         const bf16x8 b1 = *(const LAS bf16x8*)(Ks + KSWZ(32 + r32, cb));
;         p0 = __builtin_amdgcn_mfma_f32_32x32x16_bf16(b0, qr[d0], p0, 0, 0, 0);
;         p1 = __builtin_amdgcn_mfma_f32_32x32x16_bf16(b1, qr[d0], p1, 0, 0, 0); }
; }
.LBB0_2565:
	s_andn2_b64 vcc, exec, s[22:23]
	s_cbranch_vccnz .LBB0_2567
	v_add_u32_e32 v19, v217, v233
	ds_read_b128 v[20:23], v19 offset:32768
	ds_read_b128 v[24:27], v19 offset:40960
	s_waitcnt lgkmcnt(1)
	v_mfma_f32_32x32x16_bf16 v[130:145], v[20:23], v[174:177], 0
	v_add_u32_e32 v32, v217, v232
	ds_read_b128 v[28:31], v32 offset:32768
	s_waitcnt lgkmcnt(1)
	v_mfma_f32_32x32x16_bf16 v[114:129], v[24:27], v[174:177], 0
	ds_read_b128 v[20:23], v32 offset:40960
	s_waitcnt lgkmcnt(1)
	v_mfma_f32_32x32x16_bf16 v[130:145], v[28:31], v[170:173], v[130:145]
	v_add_u32_e32 v19, v217, v231
	ds_read_b128 v[24:27], v19 offset:32768
	s_waitcnt lgkmcnt(1)
	v_mfma_f32_32x32x16_bf16 v[114:129], v[20:23], v[170:173], v[114:129]
	ds_read_b128 v[28:31], v19 offset:40960
	s_waitcnt lgkmcnt(1)
	v_mfma_f32_32x32x16_bf16 v[130:145], v[24:27], v[166:169], v[130:145]
	v_add_u32_e32 v32, v217, v230
	ds_read_b128 v[20:23], v32 offset:32768
	s_waitcnt lgkmcnt(1)
	v_mfma_f32_32x32x16_bf16 v[114:129], v[28:31], v[166:169], v[114:129]
	ds_read_b128 v[24:27], v32 offset:40960
	s_waitcnt lgkmcnt(1)
	v_mfma_f32_32x32x16_bf16 v[130:145], v[20:23], v[162:165], v[130:145]
	v_add_u32_e32 v19, v217, v229
	ds_read_b128 v[28:31], v19 offset:32768
	s_waitcnt lgkmcnt(1)
	v_mfma_f32_32x32x16_bf16 v[114:129], v[24:27], v[162:165], v[114:129]
	ds_read_b128 v[20:23], v19 offset:40960
	s_waitcnt lgkmcnt(1)
	v_mfma_f32_32x32x16_bf16 v[130:145], v[28:31], v[158:161], v[130:145]
	v_add_u32_e32 v32, v217, v228
	ds_read_b128 v[24:27], v32 offset:32768
	s_waitcnt lgkmcnt(1)
	v_mfma_f32_32x32x16_bf16 v[114:129], v[20:23], v[158:161], v[114:129]
	ds_read_b128 v[28:31], v32 offset:40960
	s_waitcnt lgkmcnt(1)
	v_mfma_f32_32x32x16_bf16 v[130:145], v[24:27], v[154:157], v[130:145]
	v_add_u32_e32 v19, v217, v227
	ds_read_b128 v[20:23], v19 offset:32768
	s_waitcnt lgkmcnt(1)
	v_mfma_f32_32x32x16_bf16 v[114:129], v[28:31], v[154:157], v[114:129]
	ds_read_b128 v[24:27], v19 offset:40960
	s_waitcnt lgkmcnt(1)
	v_mfma_f32_32x32x16_bf16 v[130:145], v[20:23], v[150:153], v[130:145]
	v_add_u32_e32 v32, v217, v226
	ds_read_b128 v[28:31], v32 offset:32768
	s_waitcnt lgkmcnt(1)
	v_mfma_f32_32x32x16_bf16 v[114:129], v[24:27], v[150:153], v[114:129]
	ds_read_b128 v[20:23], v32 offset:40960
	s_waitcnt lgkmcnt(1)
	v_mfma_f32_32x32x16_bf16 v[130:145], v[28:31], v[146:149], v[130:145]
	s_waitcnt lgkmcnt(0)
	v_mfma_f32_32x32x16_bf16 v[114:129], v[20:23], v[146:149], v[114:129]
	s_branch .LBB0_2568
